# streaming reads: the final RMSNorm phase's full-line, read-once xb row loads marked non-temporal (timing-only; last experiment)
# speedup vs baseline: 1.0100x; 1.0100x over previous
.LBB0_15:
	v_ashrrev_i32_e32 v23, 31, v22
	v_lshl_add_u64 v[80:81], v[22:23], 2, s[14:15]
	v_add_co_u32_e32 v28, vcc, s77, v80
	global_load_dwordx4 v[18:21], v[80:81], off
	s_nop 0
	v_addc_co_u32_e32 v29, vcc, 0, v81, vcc
	v_add_co_u32_e32 v32, vcc, s78, v80
	global_load_dwordx4 v[28:31], v[28:29], off
	s_nop 0
	v_addc_co_u32_e32 v33, vcc, 0, v81, vcc
	v_add_co_u32_e32 v36, vcc, s79, v80
	v_lshlrev_b64 v[88:89], 11, v[22:23]
	s_nop 0
	v_addc_co_u32_e32 v37, vcc, 0, v81, vcc
	v_add_co_u32_e32 v40, vcc, s94, v80
	global_load_dwordx4 v[32:35], v[32:33], off
	s_nop 0
	global_load_dwordx4 v[36:39], v[36:37], off
	v_addc_co_u32_e32 v41, vcc, 0, v81, vcc
	v_add_co_u32_e32 v44, vcc, s95, v80
	v_lshl_add_u64 v[96:97], v[24:25], 0, v[88:89]
	s_nop 0
	v_addc_co_u32_e32 v45, vcc, 0, v81, vcc
	v_add_co_u32_e32 v48, vcc, s96, v80
	global_load_dwordx4 v[40:43], v[40:41], off
	s_nop 0
	global_load_dwordx4 v[44:47], v[44:45], off
	v_addc_co_u32_e32 v49, vcc, 0, v81, vcc
	v_add_co_u32_e32 v52, vcc, s97, v80
	v_add_u32_e32 v112, 1, v22
	s_nop 0
	v_addc_co_u32_e32 v53, vcc, 0, v81, vcc
	v_add_co_u32_e32 v56, vcc, s48, v80
	global_load_dwordx4 v[48:51], v[48:49], off
	s_nop 0
	global_load_dwordx4 v[52:55], v[52:53], off
	v_addc_co_u32_e32 v57, vcc, 0, v81, vcc
	v_add_co_u32_e32 v60, vcc, s49, v80
	v_ashrrev_i32_e32 v113, 31, v112
	s_nop 0
	v_addc_co_u32_e32 v61, vcc, 0, v81, vcc
	v_add_co_u32_e32 v64, vcc, s81, v80
	global_load_dwordx4 v[56:59], v[56:57], off
	s_nop 0
	global_load_dwordx4 v[60:63], v[60:61], off
	v_addc_co_u32_e32 v65, vcc, 0, v81, vcc
	v_add_co_u32_e32 v68, vcc, s60, v80
	v_lshlrev_b64 v[92:93], 11, v[112:113]
	s_nop 0
	v_addc_co_u32_e32 v69, vcc, 0, v81, vcc
	v_add_co_u32_e32 v72, vcc, s61, v80
	global_load_dwordx4 v[64:67], v[64:65], off
	s_nop 0
	global_load_dwordx4 v[68:71], v[68:69], off
	v_addc_co_u32_e32 v73, vcc, 0, v81, vcc
	v_add_co_u32_e32 v76, vcc, s91, v80
	v_lshl_add_u64 v[100:101], v[24:25], 0, v[92:93]
	s_nop 0
	v_addc_co_u32_e32 v77, vcc, 0, v81, vcc
	v_add_co_u32_e32 v82, vcc, s93, v80
	global_load_dwordx4 v[72:75], v[72:73], off
	s_nop 0
	global_load_dwordx4 v[76:79], v[76:77], off
	v_addc_co_u32_e32 v83, vcc, 0, v81, vcc
	v_add_co_u32_e32 v84, vcc, s33, v80
	s_movk_i32 s4, 0x7fff
	s_nop 0
	v_addc_co_u32_e32 v85, vcc, 0, v81, vcc
	global_load_dwordx4 v[80:83], v[82:83], off
	s_nop 0
	global_load_dwordx4 v[84:87], v[84:85], off
	s_waitcnt vmcnt(15)
	v_pk_add_f32 v[18:19], v[18:19], 0 op_sel_hi:[1,0]
	global_load_dwordx4 v[88:91], v[96:97], off nt
	global_load_dwordx4 v[92:95], v[100:101], off offset:1024 nt
	s_nop 0
	global_load_dwordx4 v[96:99], v[96:97], off offset:1024 nt
	v_pk_add_f32 v[20:21], v[20:21], 0 op_sel_hi:[1,0]
	global_load_dwordx4 v[100:103], v[100:101], off nt
	s_waitcnt vmcnt(18)
	v_pk_add_f32 v[18:19], v[18:19], v[28:29]
	v_pk_add_f32 v[20:21], v[20:21], v[30:31]
	v_add_u32_e32 v28, 3, v22
	v_ashrrev_i32_e32 v29, 31, v28
	s_waitcnt vmcnt(17)
	v_pk_add_f32 v[18:19], v[18:19], v[32:33]
	s_waitcnt vmcnt(16)
	v_pk_add_f32 v[18:19], v[18:19], v[36:37]
	v_pk_add_f32 v[20:21], v[20:21], v[34:35]
	s_waitcnt vmcnt(15)
	v_pk_add_f32 v[18:19], v[18:19], v[40:41]
	s_waitcnt vmcnt(14)
	v_pk_add_f32 v[18:19], v[18:19], v[44:45]
	v_pk_add_f32 v[20:21], v[20:21], v[38:39]
	s_waitcnt vmcnt(13)
	v_pk_add_f32 v[18:19], v[18:19], v[48:49]
	s_waitcnt vmcnt(12)
	v_pk_add_f32 v[18:19], v[18:19], v[52:53]
	v_pk_add_f32 v[20:21], v[20:21], v[42:43]
	v_add_u32_e32 v48, 2, v22
	v_pk_add_f32 v[20:21], v[20:21], v[46:47]
	v_ashrrev_i32_e32 v49, 31, v48
	v_pk_add_f32 v[20:21], v[20:21], v[50:51]
	s_waitcnt vmcnt(11)
	v_pk_add_f32 v[18:19], v[18:19], v[56:57]
	s_waitcnt vmcnt(10)
	v_pk_add_f32 v[18:19], v[18:19], v[60:61]
	v_pk_add_f32 v[20:21], v[20:21], v[54:55]
	s_waitcnt vmcnt(9)
	v_pk_add_f32 v[18:19], v[18:19], v[64:65]
	s_waitcnt vmcnt(8)
	v_pk_add_f32 v[18:19], v[18:19], v[68:69]
	v_pk_add_f32 v[20:21], v[20:21], v[58:59]
	s_waitcnt vmcnt(7)
	v_pk_add_f32 v[18:19], v[18:19], v[72:73]
	s_waitcnt vmcnt(6)
	v_pk_add_f32 v[18:19], v[18:19], v[76:77]
	v_pk_add_f32 v[20:21], v[20:21], v[62:63]
	s_waitcnt vmcnt(5)
	v_pk_add_f32 v[18:19], v[18:19], v[80:81]
	s_waitcnt vmcnt(4)
	v_pk_add_f32 v[18:19], v[18:19], v[84:85]
	v_pk_add_f32 v[20:21], v[20:21], v[66:67]
	v_pk_fma_f32 v[18:19], v[18:19], s[90:91], v[210:211] op_sel_hi:[1,0,0]
	v_pk_add_f32 v[20:21], v[20:21], v[70:71]
	v_mul_f32_e32 v0, 0x4b800000, v18
	v_cmp_gt_f32_e32 vcc, s10, v18
	v_cmp_gt_f32_e64 s[40:41], s10, v19
	v_pk_add_f32 v[20:21], v[20:21], v[74:75]
	v_cndmask_b32_e32 v0, v18, v0, vcc
	v_mul_f32_e32 v18, 0x4b800000, v19
	v_rsq_f32_e32 v0, v0
	v_cndmask_b32_e64 v18, v19, v18, s[40:41]
	v_rsq_f32_e32 v18, v18
	v_pk_add_f32 v[20:21], v[20:21], v[78:79]
	v_mul_f32_e32 v19, 0x45800000, v0
	v_cndmask_b32_e32 v40, v0, v19, vcc
	v_mul_f32_e32 v0, 0x45800000, v18
	v_cndmask_b32_e64 v44, v18, v0, s[40:41]
	v_lshlrev_b64 v[18:19], 11, v[48:49]
	v_lshl_add_u64 v[18:19], v[24:25], 0, v[18:19]
	global_load_dwordx4 v[104:107], v[18:19], off nt
	global_load_dwordx4 v[108:111], v[18:19], off offset:1024 nt
	v_pk_add_f32 v[20:21], v[20:21], v[82:83]
	v_lshlrev_b64 v[18:19], 11, v[28:29]
	v_pk_add_f32 v[20:21], v[20:21], v[86:87]
	v_lshl_add_u64 v[18:19], v[24:25], 0, v[18:19]
	v_pk_fma_f32 v[20:21], v[20:21], s[90:91], v[210:211] op_sel_hi:[1,0,0]
	s_waitcnt vmcnt(5)
	v_lshlrev_b32_e32 v36, 16, v89
	v_mul_f32_e32 v0, 0x4b800000, v20
	v_cmp_gt_f32_e32 vcc, s10, v20
	v_cmp_gt_f32_e64 s[40:41], s10, v21
	v_and_b32_e32 v37, 0xffff0000, v89
	v_cndmask_b32_e32 v0, v20, v0, vcc
	v_mul_f32_e32 v20, 0x4b800000, v21
	v_cndmask_b32_e64 v20, v21, v20, s[40:41]
	v_rsq_f32_e32 v34, v20
	global_load_dwordx4 v[30:33], v[18:19], off nt
	s_nop 0
	global_load_dwordx4 v[18:21], v[18:19], off offset:1024 nt
	v_rsq_f32_e32 v0, v0
	v_pk_mul_f32 v[36:37], v[40:41], v[36:37] op_sel_hi:[0,1]
	v_lshlrev_b32_e32 v46, 16, v90
	v_and_b32_e32 v47, 0xffff0000, v90
	v_mul_f32_e32 v35, 0x45800000, v0
	v_cndmask_b32_e32 v38, v0, v35, vcc
	v_mul_f32_e32 v0, 0x45800000, v34
	v_cndmask_b32_e64 v0, v34, v0, s[40:41]
	v_lshlrev_b64 v[34:35], 12, v[22:23]
	v_lshl_add_u64 v[42:43], v[26:27], 0, v[34:35]
	v_lshlrev_b32_e32 v34, 16, v88
	v_and_b32_e32 v35, 0xffff0000, v88
	v_pk_mul_f32 v[34:35], v[40:41], v[34:35] op_sel_hi:[0,1]
	v_lshlrev_b32_e32 v50, 16, v91
	v_and_b32_e32 v51, 0xffff0000, v91
	v_pk_mul_f32 v[36:37], v[8:9], v[36:37]
	v_pk_mul_f32 v[34:35], v[6:7], v[34:35]
	global_store_dwordx4 v[42:43], v[34:37], off
	v_lshlrev_b64 v[28:29], 12, v[28:29]
	v_add_u32_e32 v22, s22, v22
	v_pk_mul_f32 v[34:35], v[40:41], v[46:47] op_sel_hi:[0,1]
	v_pk_mul_f32 v[36:37], v[40:41], v[50:51] op_sel_hi:[0,1]
	v_pk_mul_f32 v[36:37], v[4:5], v[36:37]
	v_pk_mul_f32 v[34:35], v[2:3], v[34:35]
	global_store_dwordx4 v[42:43], v[34:37], off offset:16
	s_waitcnt vmcnt(7)
	v_lshlrev_b32_e32 v46, 16, v98
	v_and_b32_e32 v47, 0xffff0000, v98
	v_lshlrev_b32_e32 v34, 16, v96
	v_and_b32_e32 v35, 0xffff0000, v96
	v_lshlrev_b32_e32 v36, 16, v97
	v_and_b32_e32 v37, 0xffff0000, v97
	v_pk_mul_f32 v[34:35], v[40:41], v[34:35] op_sel_hi:[0,1]
	v_pk_mul_f32 v[36:37], v[40:41], v[36:37] op_sel_hi:[0,1]
	v_lshlrev_b32_e32 v50, 16, v99
	v_and_b32_e32 v51, 0xffff0000, v99
	v_pk_mul_f32 v[36:37], v[16:17], v[36:37]
	v_pk_mul_f32 v[34:35], v[14:15], v[34:35]
	global_store_dwordx4 v[42:43], v[34:37], off offset:2048
	v_cmp_lt_i32_e32 vcc, s4, v22
	s_or_b64 s[20:21], vcc, s[20:21]
	v_pk_mul_f32 v[34:35], v[40:41], v[46:47] op_sel_hi:[0,1]
	v_pk_mul_f32 v[36:37], v[40:41], v[50:51] op_sel_hi:[0,1]
	v_pk_mul_f32 v[36:37], v[12:13], v[36:37]
	v_pk_mul_f32 v[34:35], v[10:11], v[34:35]
	global_store_dwordx4 v[42:43], v[34:37], off offset:2064
	s_waitcnt vmcnt(8)
	v_lshlrev_b32_e32 v42, 16, v102
	v_and_b32_e32 v43, 0xffff0000, v102
	v_lshlrev_b64 v[34:35], 12, v[112:113]
	v_lshl_add_u64 v[40:41], v[26:27], 0, v[34:35]
	v_lshlrev_b32_e32 v34, 16, v100
	v_and_b32_e32 v35, 0xffff0000, v100
	v_lshlrev_b32_e32 v36, 16, v101
	v_and_b32_e32 v37, 0xffff0000, v101
	v_pk_mul_f32 v[34:35], v[44:45], v[34:35] op_sel_hi:[0,1]
	v_pk_mul_f32 v[36:37], v[44:45], v[36:37] op_sel_hi:[0,1]
	v_lshlrev_b32_e32 v46, 16, v103
	v_and_b32_e32 v47, 0xffff0000, v103
	v_pk_mul_f32 v[36:37], v[8:9], v[36:37]
	v_pk_mul_f32 v[34:35], v[6:7], v[34:35]
	global_store_dwordx4 v[40:41], v[34:37], off
	s_nop 1
	v_pk_mul_f32 v[34:35], v[44:45], v[42:43] op_sel_hi:[0,1]
	v_pk_mul_f32 v[36:37], v[44:45], v[46:47] op_sel_hi:[0,1]
	v_pk_mul_f32 v[36:37], v[4:5], v[36:37]
	v_pk_mul_f32 v[34:35], v[2:3], v[34:35]
	global_store_dwordx4 v[40:41], v[34:37], off offset:16
	v_lshlrev_b32_e32 v42, 16, v94
	v_and_b32_e32 v43, 0xffff0000, v94
	v_lshlrev_b32_e32 v34, 16, v92
	v_and_b32_e32 v35, 0xffff0000, v92
	v_lshlrev_b32_e32 v36, 16, v93
	v_and_b32_e32 v37, 0xffff0000, v93
	v_pk_mul_f32 v[34:35], v[44:45], v[34:35] op_sel_hi:[0,1]
	v_pk_mul_f32 v[36:37], v[44:45], v[36:37] op_sel_hi:[0,1]
	v_lshlrev_b32_e32 v46, 16, v95
	v_and_b32_e32 v47, 0xffff0000, v95
	v_pk_mul_f32 v[36:37], v[16:17], v[36:37]
	v_pk_mul_f32 v[34:35], v[14:15], v[34:35]
	global_store_dwordx4 v[40:41], v[34:37], off offset:2048
	s_nop 1
	v_pk_mul_f32 v[34:35], v[44:45], v[42:43] op_sel_hi:[0,1]
	v_pk_mul_f32 v[36:37], v[44:45], v[46:47] op_sel_hi:[0,1]
	v_pk_mul_f32 v[36:37], v[12:13], v[36:37]
	v_pk_mul_f32 v[34:35], v[10:11], v[34:35]
	global_store_dwordx4 v[40:41], v[34:37], off offset:2064
	s_waitcnt vmcnt(11)
	v_lshlrev_b32_e32 v42, 16, v106
	v_and_b32_e32 v43, 0xffff0000, v106
	v_lshlrev_b64 v[34:35], 12, v[48:49]
	v_lshl_add_u64 v[40:41], v[26:27], 0, v[34:35]
	v_lshlrev_b32_e32 v34, 16, v104
	v_and_b32_e32 v35, 0xffff0000, v104
	v_lshlrev_b32_e32 v36, 16, v105
	v_and_b32_e32 v37, 0xffff0000, v105
	v_pk_mul_f32 v[34:35], v[38:39], v[34:35] op_sel_hi:[0,1]
	v_pk_mul_f32 v[36:37], v[38:39], v[36:37] op_sel_hi:[0,1]
	v_lshlrev_b32_e32 v44, 16, v107
	v_and_b32_e32 v45, 0xffff0000, v107
	v_pk_mul_f32 v[36:37], v[8:9], v[36:37]
	v_pk_mul_f32 v[34:35], v[6:7], v[34:35]
	global_store_dwordx4 v[40:41], v[34:37], off
	s_nop 1
	v_pk_mul_f32 v[34:35], v[38:39], v[42:43] op_sel_hi:[0,1]
	v_pk_mul_f32 v[36:37], v[38:39], v[44:45] op_sel_hi:[0,1]
	v_pk_mul_f32 v[36:37], v[4:5], v[36:37]
	v_pk_mul_f32 v[34:35], v[2:3], v[34:35]
	global_store_dwordx4 v[40:41], v[34:37], off offset:16
	s_waitcnt vmcnt(12)
	v_lshlrev_b32_e32 v42, 16, v110
	v_and_b32_e32 v43, 0xffff0000, v110
	v_lshlrev_b32_e32 v34, 16, v108
	v_and_b32_e32 v35, 0xffff0000, v108
	v_lshlrev_b32_e32 v36, 16, v109
	v_and_b32_e32 v37, 0xffff0000, v109
	v_pk_mul_f32 v[34:35], v[38:39], v[34:35] op_sel_hi:[0,1]
	v_pk_mul_f32 v[36:37], v[38:39], v[36:37] op_sel_hi:[0,1]
	v_lshlrev_b32_e32 v44, 16, v111
	v_and_b32_e32 v45, 0xffff0000, v111
	v_pk_mul_f32 v[36:37], v[16:17], v[36:37]
	v_pk_mul_f32 v[34:35], v[14:15], v[34:35]
	global_store_dwordx4 v[40:41], v[34:37], off offset:2048
	s_nop 1
	v_pk_mul_f32 v[34:35], v[38:39], v[42:43] op_sel_hi:[0,1]
	v_pk_mul_f32 v[36:37], v[38:39], v[44:45] op_sel_hi:[0,1]
	v_pk_mul_f32 v[36:37], v[12:13], v[36:37]
	v_pk_mul_f32 v[34:35], v[10:11], v[34:35]
	global_store_dwordx4 v[40:41], v[34:37], off offset:2064
	s_nop 1
	v_lshl_add_u64 v[34:35], v[26:27], 0, v[28:29]
	s_waitcnt vmcnt(13)
	v_lshlrev_b32_e32 v28, 16, v30
	v_and_b32_e32 v29, 0xffff0000, v30
	v_lshlrev_b32_e32 v30, 16, v31
	v_and_b32_e32 v31, 0xffff0000, v31
	v_pk_mul_f32 v[28:29], v[0:1], v[28:29] op_sel_hi:[0,1]
	v_pk_mul_f32 v[30:31], v[0:1], v[30:31] op_sel_hi:[0,1]
	v_lshlrev_b32_e32 v36, 16, v32
	v_and_b32_e32 v37, 0xffff0000, v32
	v_lshlrev_b32_e32 v32, 16, v33
	v_and_b32_e32 v33, 0xffff0000, v33
	v_pk_mul_f32 v[30:31], v[8:9], v[30:31]
	v_pk_mul_f32 v[28:29], v[6:7], v[28:29]
	global_store_dwordx4 v[34:35], v[28:31], off
	s_nop 1
	v_pk_mul_f32 v[28:29], v[0:1], v[36:37] op_sel_hi:[0,1]
	v_pk_mul_f32 v[30:31], v[0:1], v[32:33] op_sel_hi:[0,1]
	v_pk_mul_f32 v[30:31], v[4:5], v[30:31]
	v_pk_mul_f32 v[28:29], v[2:3], v[28:29]
	global_store_dwordx4 v[34:35], v[28:31], off offset:16
	s_waitcnt vmcnt(14)
	v_lshlrev_b32_e32 v32, 16, v21
	v_and_b32_e32 v33, 0xffff0000, v21
	v_lshlrev_b32_e32 v28, 16, v18
	v_and_b32_e32 v29, 0xffff0000, v18
	v_lshlrev_b32_e32 v18, 16, v19
	v_and_b32_e32 v19, 0xffff0000, v19
	v_pk_mul_f32 v[28:29], v[0:1], v[28:29] op_sel_hi:[0,1]
	v_pk_mul_f32 v[18:19], v[0:1], v[18:19] op_sel_hi:[0,1]
	v_lshlrev_b32_e32 v30, 16, v20
	v_and_b32_e32 v31, 0xffff0000, v20
	v_pk_mul_f32 v[20:21], v[16:17], v[18:19]
	v_pk_mul_f32 v[18:19], v[14:15], v[28:29]
	global_store_dwordx4 v[34:35], v[18:21], off offset:2048
	s_nop 1
	v_pk_mul_f32 v[18:19], v[0:1], v[30:31] op_sel_hi:[0,1]
	v_pk_mul_f32 v[20:21], v[0:1], v[32:33] op_sel_hi:[0,1]
	v_pk_mul_f32 v[20:21], v[12:13], v[20:21]
	v_pk_mul_f32 v[18:19], v[10:11], v[18:19]
	global_store_dwordx4 v[34:35], v[18:21], off offset:2064
	s_andn2_b64 exec, exec, s[20:21]
	s_cbranch_execnz .LBB0_15
